# layer 0's w_out/gate/up/down/glu transposes also deferred to the in-proj(0) idle workgroups (only w_in, w_mod and tables remain in phase 0)
# baseline (speedup 1.0000x reference)
; #define INP(i) ((const float*)ld_ptr(pb, (i)))
; __global__ void __launch_bounds__(512, 2) hybrid_fwd(Params P) {
;     ...
;         for (int it = gw; it < DEPTH * I_LAYER; it += NGW) {
;             const int l = it / I_LAYER; int r = it % I_LAYER;
;             if (r < I_IN) { const int kb = r / 48, nbk = r % 48; transpose_item(INP(13) + (size_t)l * D * NIN, D, NIN, WIN + (size_t)l * NIN * D, nbk * 32, kb * 64, win_dst_row(nbk * 32), scr, lane); continue; } r -= I_IN;
.LBB0_76:
	s_mul_hi_i32 s0, s10, 0x79d06a97
	s_lshr_b32 s2, s0, 31
	s_ashr_i32 s0, s0, 12
	s_add_i32 s2, s0, s2
	s_mul_i32 s0, s2, 0xffffde60
	s_add_i32 s8, s10, s0
	s_cmp_lt_i32 s2, 1
	s_cbranch_scc0 .Lp0_l1
	s_cmpk_lt_u32 s8, 0x300
	s_cbranch_scc1 .Lp0_keep
	s_cmpk_lt_u32 s8, 0x15a0
	s_cbranch_scc1 .LBB0_75
	s_branch .Lp0_keep
.Lp0_l1:
	s_cmpk_lt_u32 s8, 0x15a0
	s_cbranch_scc1 .LBB0_75

; #define INP(i) ((const float*)ld_ptr(pb, (i)))
; __global__ void __launch_bounds__(512, 2) hybrid_fwd(Params P) {
;     ...
;         for (int it = gw; it < DEPTH * I_LAYER; it += NGW) {
;             const int l = it / I_LAYER; int r = it % I_LAYER;
;             if (r < I_IN) { const int kb = r / 48, nbk = r % 48; transpose_item(INP(13) + (size_t)l * D * NIN, D, NIN, WIN + (size_t)l * NIN * D, nbk * 32, kb * 64, win_dst_row(nbk * 32), scr, lane); continue; } r -= I_IN;
;             if (r < I_OUT) { const int kb = r / 32, nbk = r % 32; transpose_item(INP(29) + (size_t)l * D * D, D, D, WOUT + (size_t)l * D * D, nbk * 32, kb * 64, nbk * 32, scr, lane); continue; } r -= I_OUT;
;             if (r < I_G) { const int kb = r / 88, nbk = r % 88, n0 = nbk * 32; transpose_item(INP(30) + (size_t)l * D * DFF, D, DFF, WGU + (size_t)l * NGU * D, n0, kb * 64, 256 * (n0 >> 7) + (n0 & 127), scr, lane); continue; } r -= I_G;
;             if (r < I_G) { const int kb = r / 88, nbk = r % 88, n0 = nbk * 32; transpose_item(INP(31) + (size_t)l * D * DFF, D, DFF, WGU + (size_t)l * NGU * D, n0, kb * 64, 256 * (n0 >> 7) + 128 + (n0 & 127), scr, lane); continue; } r -= I_G;
;             if (r < I_DN) { const int kb = r / 32, nbk = r % 32; transpose_item(INP(32) + (size_t)l * DFF * D, DFF, D, WDN + (size_t)l * D * DFF, nbk * 32, kb * 64, nbk * 32, scr, lane); continue; } r -= I_DN;
;             if (r < I_GLU) { const int kb = r / 8, nbk = r % 8; transpose_item(INP(23) + (size_t)l * 65536, 256, 256, WGLU + (size_t)l * 65536, nbk * 32, kb * 64, nbk * 32, scr, lane); continue; } r -= I_GLU;
.Ltr_a_end:
	s_cmp_eq_u32 s96, 0
	s_cbranch_scc0 .Ltr_a0_end
	s_mov_b32 s37, 0
	v_mbcnt_lo_u32_b32 v6, -1, 0
	v_mbcnt_hi_u32_b32 v6, -1, v6
	v_lshrrev_b32_e32 v7, 5, v6
	v_and_b32_e32 v6, 31, v6
	s_add_u32 s0, s29, 768
	s_mov_b32 s1, 5536
	s_cmp_lt_u32 s0, s1
	s_cbranch_scc0 .Ltr_a0_end
